# P5 K-loop: LDS-DMA staging issued at the start of the load segment, before the fragment reads
# speedup vs baseline: 1.0013x; 1.0013x over previous
.LBB0_1134:
	s_ashr_i32 s57, s56, 31
	s_lshl_b64 s[60:61], s[56:57], 19
	s_add_u32 s60, s42, s60
	s_addc_u32 s61, s43, s61
	s_and_b64 s[62:63], s[10:11], exec
	s_cselect_b32 s57, s61, s27
	s_cselect_b32 s79, s60, s26
	s_ashr_i32 s59, s58, 31
	s_lshl_b64 s[62:63], s[58:59], 19
	v_readlane_b32 s70, v254, 7
	v_readlane_b32 s71, v254, 8
	s_add_u32 s62, s70, s62
	s_addc_u32 s63, s71, s63
	s_and_b64 s[70:71], s[10:11], exec
	s_cselect_b32 s59, s63, s69
	s_cselect_b32 s80, s62, s68
	s_add_u32 s81, s68, 0x100
	v_lshl_add_u64 v[138:139], s[26:27], 0, v[132:133]
	s_addc_u32 s82, s69, 0
	s_mov_b32 s83, -2
	s_mov_b64 s[68:69], 0
	s_add_u32 s70, s26, s68
	s_addc_u32 s71, s27, s69
	s_add_u32 s70, s70, 0x100
	s_addc_u32 s71, s71, 0
	s_add_u32 s84, s81, s68
	s_addc_u32 s85, s82, s69
	s_cmpk_eq_i32 s68, 0x700
	s_cselect_b32 s85, s59, s85
	s_cselect_b32 s84, s80, s84
	s_cselect_b32 s71, s57, s71
	s_cselect_b32 s70, s79, s70
	v_lshl_add_u64 v[140:141], v[138:139], 0, s[68:69]
	v_lshl_add_u64 v[242:243], v[140:141], 0, s[22:23]
	s_add_i32 m0, s34, 0x8000
	s_mov_b64 s[86:87], 0x20080
	global_load_lds_dwordx4 v[242:243], off
	v_lshl_add_u64 v[242:243], v[140:141], 0, s[86:87]
	s_add_i32 m0, s34, 0xa000
	s_mov_b64 s[86:87], 0x60080
	global_load_lds_dwordx4 v[242:243], off
	v_lshl_add_u64 v[242:243], v[140:141], 0, s[24:25]
	s_add_i32 m0, s34, 0xc000
	v_lshl_add_u64 v[140:141], v[140:141], 0, s[86:87]
	global_load_lds_dwordx4 v[242:243], off
	s_add_i32 m0, s34, 0xe000
	s_nop 0
	global_load_lds_dwordx4 v[140:141], off
	ds_read_b128 v[168:171], v145
	ds_read_b128 v[174:177], v146
	ds_read_b128 v[178:181], v147
	ds_read_b128 v[182:185], v148
	ds_read_b128 v[194:197], v149
	ds_read_b128 v[198:201], v150
	ds_read_b128 v[202:205], v151
	ds_read_b128 v[206:209], v152
	ds_read_b128 v[210:213], v153
	ds_read_b128 v[214:217], v153 offset:2048
	ds_read_b128 v[218:221], v154
	ds_read_b128 v[222:225], v154 offset:2048
	ds_read_b128 v[226:229], v153 offset:4096
	ds_read_b128 v[230:233], v153 offset:6144
	ds_read_b128 v[234:237], v154 offset:4096
	ds_read_b128 v[238:241], v154 offset:6144
	s_waitcnt lgkmcnt(0)
	s_barrier
	v_mfma_f32_16x16x32_bf16 v[128:131], v[168:171], v[210:213], 0
	v_mfma_f32_16x16x32_bf16 v[124:127], v[178:181], v[210:213], 0
	v_mfma_f32_16x16x32_bf16 v[112:115], v[168:171], v[214:217], 0
	v_mfma_f32_16x16x32_bf16 v[108:111], v[178:181], v[214:217], 0
	v_mfma_f32_16x16x32_bf16 v[96:99], v[168:171], v[226:229], 0
	v_mfma_f32_16x16x32_bf16 v[92:95], v[178:181], v[226:229], 0
	v_mfma_f32_16x16x32_bf16 v[80:83], v[168:171], v[230:233], 0
	v_mfma_f32_16x16x32_bf16 v[76:79], v[178:181], v[230:233], 0
	v_mfma_f32_16x16x32_bf16 v[128:131], v[174:177], v[218:221], v[128:131]
	v_mfma_f32_16x16x32_bf16 v[124:127], v[182:185], v[218:221], v[124:127]
	v_mfma_f32_16x16x32_bf16 v[112:115], v[174:177], v[222:225], v[112:115]
	v_mfma_f32_16x16x32_bf16 v[108:111], v[182:185], v[222:225], v[108:111]
	v_mfma_f32_16x16x32_bf16 v[96:99], v[174:177], v[234:237], v[96:99]
	v_mfma_f32_16x16x32_bf16 v[92:95], v[182:185], v[234:237], v[92:95]
	v_mfma_f32_16x16x32_bf16 v[80:83], v[174:177], v[238:241], v[80:83]
	v_mfma_f32_16x16x32_bf16 v[76:79], v[182:185], v[238:241], v[76:79]
	v_mfma_f32_16x16x32_bf16 v[120:123], v[194:197], v[210:213], 0
	v_mfma_f32_16x16x32_bf16 v[116:119], v[202:205], v[210:213], 0
	v_mfma_f32_16x16x32_bf16 v[104:107], v[194:197], v[214:217], 0
	v_mfma_f32_16x16x32_bf16 v[100:103], v[202:205], v[214:217], 0
	v_mfma_f32_16x16x32_bf16 v[88:91], v[194:197], v[226:229], 0
	v_mfma_f32_16x16x32_bf16 v[84:87], v[202:205], v[226:229], 0
	v_mfma_f32_16x16x32_bf16 v[72:75], v[194:197], v[230:233], 0
	v_mfma_f32_16x16x32_bf16 v[68:71], v[202:205], v[230:233], 0
	v_mfma_f32_16x16x32_bf16 v[120:123], v[198:201], v[218:221], v[120:123]
	v_mfma_f32_16x16x32_bf16 v[116:119], v[206:209], v[218:221], v[116:119]
	v_mfma_f32_16x16x32_bf16 v[104:107], v[198:201], v[222:225], v[104:107]
	v_mfma_f32_16x16x32_bf16 v[100:103], v[206:209], v[222:225], v[100:103]
	v_mfma_f32_16x16x32_bf16 v[88:91], v[198:201], v[234:237], v[88:91]
	v_mfma_f32_16x16x32_bf16 v[84:87], v[206:209], v[234:237], v[84:87]
	v_mfma_f32_16x16x32_bf16 v[72:75], v[198:201], v[238:241], v[72:75]
	v_mfma_f32_16x16x32_bf16 v[68:71], v[206:209], v[238:241], v[68:71]
	s_barrier
	v_lshl_add_u64 v[140:141], s[84:85], 0, v[158:159]
	s_add_i32 s84, s67, s3
	s_mov_b32 m0, s84
	global_load_lds_dwordx4 v[140:141], off
	v_lshl_add_u64 v[242:243], v[140:141], 0, s[0:1]
	s_add_i32 m0, s84, 0x2000
	s_add_i32 s84, s72, s3
	global_load_lds_dwordx4 v[242:243], off
	v_lshl_add_u64 v[242:243], v[140:141], 0, s[12:13]
	s_mov_b32 m0, s84
	s_nop 0
	global_load_lds_dwordx4 v[242:243], off
	v_lshl_add_u64 v[242:243], v[140:141], 0, s[14:15]
	s_add_i32 m0, s84, 0x2000
	s_nop 0
	global_load_lds_dwordx4 v[242:243], off
	ds_read_b128 v[210:213], v153 offset:16384
	ds_read_b128 v[214:217], v153 offset:18432
	ds_read_b128 v[218:221], v154 offset:16384
	ds_read_b128 v[222:225], v154 offset:18432
	ds_read_b128 v[226:229], v153 offset:20480
	ds_read_b128 v[230:233], v153 offset:22528
	ds_read_b128 v[234:237], v154 offset:20480
	ds_read_b128 v[238:241], v154 offset:22528
	s_waitcnt vmcnt(4)
	s_waitcnt lgkmcnt(0)
	s_barrier
	v_mfma_f32_16x16x32_bf16 v[64:67], v[168:171], v[210:213], 0
	v_mfma_f32_16x16x32_bf16 v[60:63], v[178:181], v[210:213], 0
	v_mfma_f32_16x16x32_bf16 v[48:51], v[168:171], v[214:217], 0
	v_mfma_f32_16x16x32_bf16 v[44:47], v[178:181], v[214:217], 0
	v_mfma_f32_16x16x32_bf16 v[32:35], v[168:171], v[226:229], 0
	v_mfma_f32_16x16x32_bf16 v[28:31], v[178:181], v[226:229], 0
	v_mfma_f32_16x16x32_bf16 v[16:19], v[168:171], v[230:233], 0
	v_mfma_f32_16x16x32_bf16 v[12:15], v[178:181], v[230:233], 0
	v_mfma_f32_16x16x32_bf16 v[64:67], v[174:177], v[218:221], v[64:67]
	v_mfma_f32_16x16x32_bf16 v[60:63], v[182:185], v[218:221], v[60:63]
	v_mfma_f32_16x16x32_bf16 v[48:51], v[174:177], v[222:225], v[48:51]
	v_mfma_f32_16x16x32_bf16 v[44:47], v[182:185], v[222:225], v[44:47]
	v_mfma_f32_16x16x32_bf16 v[32:35], v[174:177], v[234:237], v[32:35]
	v_mfma_f32_16x16x32_bf16 v[28:31], v[182:185], v[234:237], v[28:31]
	v_mfma_f32_16x16x32_bf16 v[16:19], v[174:177], v[238:241], v[16:19]
	v_mfma_f32_16x16x32_bf16 v[12:15], v[182:185], v[238:241], v[12:15]
	v_mfma_f32_16x16x32_bf16 v[56:59], v[194:197], v[210:213], 0
	v_mfma_f32_16x16x32_bf16 v[52:55], v[202:205], v[210:213], 0
	v_mfma_f32_16x16x32_bf16 v[40:43], v[194:197], v[214:217], 0
	v_mfma_f32_16x16x32_bf16 v[36:39], v[202:205], v[214:217], 0
	v_mfma_f32_16x16x32_bf16 v[24:27], v[194:197], v[226:229], 0
	v_mfma_f32_16x16x32_bf16 v[20:23], v[202:205], v[226:229], 0
	v_mfma_f32_16x16x32_bf16 v[8:11], v[194:197], v[230:233], 0
	v_mfma_f32_16x16x32_bf16 v[4:7], v[202:205], v[230:233], 0
	v_mfma_f32_16x16x32_bf16 v[56:59], v[198:201], v[218:221], v[56:59]
	v_mfma_f32_16x16x32_bf16 v[52:55], v[206:209], v[218:221], v[52:55]
	v_mfma_f32_16x16x32_bf16 v[40:43], v[198:201], v[222:225], v[40:43]
	v_mfma_f32_16x16x32_bf16 v[36:39], v[206:209], v[222:225], v[36:39]
	v_mfma_f32_16x16x32_bf16 v[24:27], v[198:201], v[234:237], v[24:27]
	v_mfma_f32_16x16x32_bf16 v[20:23], v[206:209], v[234:237], v[20:23]
	v_mfma_f32_16x16x32_bf16 v[8:11], v[198:201], v[238:241], v[8:11]
	v_mfma_f32_16x16x32_bf16 v[4:7], v[206:209], v[238:241], v[4:7]
	s_barrier
	s_mov_b32 m0, s34
	v_lshl_add_u64 v[242:243], s[70:71], 0, v[0:1]
	global_load_lds_dwordx4 v[242:243], off
	v_lshl_add_u64 v[244:245], v[242:243], 0, s[16:17]
	s_mov_b32 m0, s35
	s_nop 0
	global_load_lds_dwordx4 v[244:245], off
	v_lshl_add_u64 v[244:245], v[242:243], 0, s[0:1]
	s_mov_b32 m0, s38
	v_lshl_add_u64 v[242:243], v[242:243], 0, s[18:19]
	global_load_lds_dwordx4 v[244:245], off
	s_mov_b32 m0, s39
	s_nop 0
	global_load_lds_dwordx4 v[242:243], off
	ds_read_b128 v[168:171], v163
	ds_read_b128 v[174:177], v164
	ds_read_b128 v[178:181], v155
	ds_read_b128 v[182:185], v160
	ds_read_b128 v[194:197], v165
	ds_read_b128 v[198:201], v166
	ds_read_b128 v[202:205], v161
	ds_read_b128 v[206:209], v162
	ds_read_b128 v[210:213], v153 offset:32768
	ds_read_b128 v[214:217], v153 offset:34816
	ds_read_b128 v[218:221], v154 offset:32768
	ds_read_b128 v[222:225], v154 offset:34816
	ds_read_b128 v[226:229], v153 offset:36864
	ds_read_b128 v[230:233], v153 offset:38912
	ds_read_b128 v[234:237], v154 offset:36864
	ds_read_b128 v[238:241], v154 offset:38912
	s_waitcnt vmcnt(8)
	s_waitcnt lgkmcnt(0)
	s_barrier
	v_mfma_f32_16x16x32_bf16 v[128:131], v[168:171], v[210:213], v[128:131]
	v_mfma_f32_16x16x32_bf16 v[124:127], v[178:181], v[210:213], v[124:127]
	v_mfma_f32_16x16x32_bf16 v[112:115], v[168:171], v[214:217], v[112:115]
	v_mfma_f32_16x16x32_bf16 v[108:111], v[178:181], v[214:217], v[108:111]
	v_mfma_f32_16x16x32_bf16 v[96:99], v[168:171], v[226:229], v[96:99]
	v_mfma_f32_16x16x32_bf16 v[92:95], v[178:181], v[226:229], v[92:95]
	v_mfma_f32_16x16x32_bf16 v[80:83], v[168:171], v[230:233], v[80:83]
	v_mfma_f32_16x16x32_bf16 v[76:79], v[178:181], v[230:233], v[76:79]
	v_mfma_f32_16x16x32_bf16 v[128:131], v[174:177], v[218:221], v[128:131]
	v_mfma_f32_16x16x32_bf16 v[124:127], v[182:185], v[218:221], v[124:127]
	v_mfma_f32_16x16x32_bf16 v[112:115], v[174:177], v[222:225], v[112:115]
	v_mfma_f32_16x16x32_bf16 v[108:111], v[182:185], v[222:225], v[108:111]
	v_mfma_f32_16x16x32_bf16 v[96:99], v[174:177], v[234:237], v[96:99]
	v_mfma_f32_16x16x32_bf16 v[92:95], v[182:185], v[234:237], v[92:95]
	v_mfma_f32_16x16x32_bf16 v[80:83], v[174:177], v[238:241], v[80:83]
	v_mfma_f32_16x16x32_bf16 v[76:79], v[182:185], v[238:241], v[76:79]
	v_mfma_f32_16x16x32_bf16 v[120:123], v[194:197], v[210:213], v[120:123]
	v_mfma_f32_16x16x32_bf16 v[116:119], v[202:205], v[210:213], v[116:119]
	v_mfma_f32_16x16x32_bf16 v[104:107], v[194:197], v[214:217], v[104:107]
	v_mfma_f32_16x16x32_bf16 v[100:103], v[202:205], v[214:217], v[100:103]
	v_mfma_f32_16x16x32_bf16 v[88:91], v[194:197], v[226:229], v[88:91]
	v_mfma_f32_16x16x32_bf16 v[84:87], v[202:205], v[226:229], v[84:87]
	v_mfma_f32_16x16x32_bf16 v[72:75], v[194:197], v[230:233], v[72:75]
	v_mfma_f32_16x16x32_bf16 v[68:71], v[202:205], v[230:233], v[68:71]
	v_mfma_f32_16x16x32_bf16 v[120:123], v[198:201], v[218:221], v[120:123]
	v_mfma_f32_16x16x32_bf16 v[116:119], v[206:209], v[218:221], v[116:119]
	v_mfma_f32_16x16x32_bf16 v[104:107], v[198:201], v[222:225], v[104:107]
	v_mfma_f32_16x16x32_bf16 v[100:103], v[206:209], v[222:225], v[100:103]
	v_mfma_f32_16x16x32_bf16 v[88:91], v[198:201], v[234:237], v[88:91]
	v_mfma_f32_16x16x32_bf16 v[84:87], v[206:209], v[234:237], v[84:87]
	v_mfma_f32_16x16x32_bf16 v[72:75], v[198:201], v[238:241], v[72:75]
	v_mfma_f32_16x16x32_bf16 v[68:71], v[206:209], v[238:241], v[68:71]
	s_barrier
	s_add_i32 s70, s73, s3
	v_lshl_add_u64 v[242:243], v[140:141], 0, s[22:23]
	s_mov_b32 m0, s70
	global_load_lds_dwordx4 v[242:243], off
	v_lshl_add_u64 v[242:243], v[140:141], 0, s[24:25]
	s_add_i32 m0, s70, 0x2000
	s_add_i32 s70, s77, s3
	global_load_lds_dwordx4 v[242:243], off
	v_lshl_add_u64 v[242:243], v[140:141], 0, s[28:29]
	s_mov_b32 m0, s70
	v_lshl_add_u64 v[140:141], v[140:141], 0, s[36:37]
	global_load_lds_dwordx4 v[242:243], off
	s_add_i32 m0, s70, 0x2000
	s_nop 0
	global_load_lds_dwordx4 v[140:141], off
	ds_read_b128 v[210:213], v153 offset:49152
	ds_read_b128 v[214:217], v153 offset:51200
	ds_read_b128 v[218:221], v154 offset:49152
	ds_read_b128 v[222:225], v154 offset:51200
	ds_read_b128 v[226:229], v153 offset:53248
	ds_read_b128 v[230:233], v153 offset:55296
	ds_read_b128 v[234:237], v154 offset:53248
	ds_read_b128 v[238:241], v154 offset:55296
	s_waitcnt vmcnt(4)
	s_waitcnt lgkmcnt(0)
	s_barrier
	v_mfma_f32_16x16x32_bf16 v[64:67], v[168:171], v[210:213], v[64:67]
	v_mfma_f32_16x16x32_bf16 v[60:63], v[178:181], v[210:213], v[60:63]
	v_mfma_f32_16x16x32_bf16 v[48:51], v[168:171], v[214:217], v[48:51]
	v_mfma_f32_16x16x32_bf16 v[44:47], v[178:181], v[214:217], v[44:47]
	v_mfma_f32_16x16x32_bf16 v[32:35], v[168:171], v[226:229], v[32:35]
	v_mfma_f32_16x16x32_bf16 v[28:31], v[178:181], v[226:229], v[28:31]
	v_mfma_f32_16x16x32_bf16 v[16:19], v[168:171], v[230:233], v[16:19]
	v_mfma_f32_16x16x32_bf16 v[12:15], v[178:181], v[230:233], v[12:15]
	v_mfma_f32_16x16x32_bf16 v[64:67], v[174:177], v[218:221], v[64:67]
	v_mfma_f32_16x16x32_bf16 v[60:63], v[182:185], v[218:221], v[60:63]
	v_mfma_f32_16x16x32_bf16 v[48:51], v[174:177], v[222:225], v[48:51]
	v_mfma_f32_16x16x32_bf16 v[44:47], v[182:185], v[222:225], v[44:47]
	v_mfma_f32_16x16x32_bf16 v[32:35], v[174:177], v[234:237], v[32:35]
	v_mfma_f32_16x16x32_bf16 v[28:31], v[182:185], v[234:237], v[28:31]
	v_mfma_f32_16x16x32_bf16 v[16:19], v[174:177], v[238:241], v[16:19]
	v_mfma_f32_16x16x32_bf16 v[12:15], v[182:185], v[238:241], v[12:15]
	v_mfma_f32_16x16x32_bf16 v[56:59], v[194:197], v[210:213], v[56:59]
	v_mfma_f32_16x16x32_bf16 v[52:55], v[202:205], v[210:213], v[52:55]
	v_mfma_f32_16x16x32_bf16 v[40:43], v[194:197], v[214:217], v[40:43]
	v_mfma_f32_16x16x32_bf16 v[36:39], v[202:205], v[214:217], v[36:39]
	v_mfma_f32_16x16x32_bf16 v[24:27], v[194:197], v[226:229], v[24:27]
	v_mfma_f32_16x16x32_bf16 v[20:23], v[202:205], v[226:229], v[20:23]
	v_mfma_f32_16x16x32_bf16 v[8:11], v[194:197], v[230:233], v[8:11]
	v_mfma_f32_16x16x32_bf16 v[4:7], v[202:205], v[230:233], v[4:7]
	v_mfma_f32_16x16x32_bf16 v[56:59], v[198:201], v[218:221], v[56:59]
	v_mfma_f32_16x16x32_bf16 v[52:55], v[206:209], v[218:221], v[52:55]
	v_mfma_f32_16x16x32_bf16 v[40:43], v[198:201], v[222:225], v[40:43]
	v_mfma_f32_16x16x32_bf16 v[36:39], v[206:209], v[222:225], v[36:39]
	v_mfma_f32_16x16x32_bf16 v[24:27], v[198:201], v[234:237], v[24:27]
	v_mfma_f32_16x16x32_bf16 v[20:23], v[206:209], v[234:237], v[20:23]
	v_mfma_f32_16x16x32_bf16 v[8:11], v[198:201], v[238:241], v[8:11]
	v_mfma_f32_16x16x32_bf16 v[4:7], v[206:209], v[238:241], v[4:7]
	s_barrier
	s_add_i32 s83, s83, 2
	s_add_u32 s68, s68, 0x100
	s_addc_u32 s69, s69, 0
	s_cmp_gt_u32 s83, 13
.LBB0_1135:
	s_add_u32 s70, s26, s68
	s_addc_u32 s71, s27, s69
	s_add_u32 s70, s70, 0x100
	s_addc_u32 s71, s71, 0
	s_add_u32 s84, s81, s68
	s_addc_u32 s85, s82, s69
	s_cmpk_eq_i32 s68, 0x700
	s_cselect_b32 s85, s59, s85
	s_cselect_b32 s84, s80, s84
	s_cselect_b32 s71, s57, s71
	s_cselect_b32 s70, s79, s70
	v_lshl_add_u64 v[140:141], v[138:139], 0, s[68:69]
	v_lshl_add_u64 v[242:243], v[140:141], 0, s[22:23]
	s_add_i32 m0, s34, 0x8000
	s_mov_b64 s[86:87], 0x20080
	global_load_lds_dwordx4 v[242:243], off
	v_lshl_add_u64 v[242:243], v[140:141], 0, s[86:87]
	s_add_i32 m0, s34, 0xa000
	s_mov_b64 s[86:87], 0x60080
	global_load_lds_dwordx4 v[242:243], off
	v_lshl_add_u64 v[242:243], v[140:141], 0, s[24:25]
	s_add_i32 m0, s34, 0xc000
	v_lshl_add_u64 v[140:141], v[140:141], 0, s[86:87]
	global_load_lds_dwordx4 v[242:243], off
	s_add_i32 m0, s34, 0xe000
	s_nop 0
	global_load_lds_dwordx4 v[140:141], off
	ds_read_b128 v[168:171], v145
	ds_read_b128 v[174:177], v146
	ds_read_b128 v[178:181], v147
	ds_read_b128 v[182:185], v148
	ds_read_b128 v[194:197], v149
	ds_read_b128 v[198:201], v150
	ds_read_b128 v[202:205], v151
	ds_read_b128 v[206:209], v152
	ds_read_b128 v[210:213], v153
	ds_read_b128 v[214:217], v153 offset:2048
	ds_read_b128 v[218:221], v154
	ds_read_b128 v[222:225], v154 offset:2048
	ds_read_b128 v[226:229], v153 offset:4096
	ds_read_b128 v[230:233], v153 offset:6144
	ds_read_b128 v[234:237], v154 offset:4096
	ds_read_b128 v[238:241], v154 offset:6144
	s_waitcnt vmcnt(8)
	s_waitcnt lgkmcnt(0)
	s_barrier
	v_mfma_f32_16x16x32_bf16 v[128:131], v[168:171], v[210:213], v[128:131]
	v_mfma_f32_16x16x32_bf16 v[124:127], v[178:181], v[210:213], v[124:127]
	v_mfma_f32_16x16x32_bf16 v[112:115], v[168:171], v[214:217], v[112:115]
	v_mfma_f32_16x16x32_bf16 v[108:111], v[178:181], v[214:217], v[108:111]
	v_mfma_f32_16x16x32_bf16 v[96:99], v[168:171], v[226:229], v[96:99]
	v_mfma_f32_16x16x32_bf16 v[92:95], v[178:181], v[226:229], v[92:95]
	v_mfma_f32_16x16x32_bf16 v[80:83], v[168:171], v[230:233], v[80:83]
	v_mfma_f32_16x16x32_bf16 v[76:79], v[178:181], v[230:233], v[76:79]
	v_mfma_f32_16x16x32_bf16 v[128:131], v[174:177], v[218:221], v[128:131]
	v_mfma_f32_16x16x32_bf16 v[124:127], v[182:185], v[218:221], v[124:127]
	v_mfma_f32_16x16x32_bf16 v[112:115], v[174:177], v[222:225], v[112:115]
	v_mfma_f32_16x16x32_bf16 v[108:111], v[182:185], v[222:225], v[108:111]
	v_mfma_f32_16x16x32_bf16 v[96:99], v[174:177], v[234:237], v[96:99]
	v_mfma_f32_16x16x32_bf16 v[92:95], v[182:185], v[234:237], v[92:95]
	v_mfma_f32_16x16x32_bf16 v[80:83], v[174:177], v[238:241], v[80:83]
	v_mfma_f32_16x16x32_bf16 v[76:79], v[182:185], v[238:241], v[76:79]
	v_mfma_f32_16x16x32_bf16 v[120:123], v[194:197], v[210:213], v[120:123]
	v_mfma_f32_16x16x32_bf16 v[116:119], v[202:205], v[210:213], v[116:119]
	v_mfma_f32_16x16x32_bf16 v[104:107], v[194:197], v[214:217], v[104:107]
	v_mfma_f32_16x16x32_bf16 v[100:103], v[202:205], v[214:217], v[100:103]
	v_mfma_f32_16x16x32_bf16 v[88:91], v[194:197], v[226:229], v[88:91]
	v_mfma_f32_16x16x32_bf16 v[84:87], v[202:205], v[226:229], v[84:87]
	v_mfma_f32_16x16x32_bf16 v[72:75], v[194:197], v[230:233], v[72:75]
	v_mfma_f32_16x16x32_bf16 v[68:71], v[202:205], v[230:233], v[68:71]
	v_mfma_f32_16x16x32_bf16 v[120:123], v[198:201], v[218:221], v[120:123]
	v_mfma_f32_16x16x32_bf16 v[116:119], v[206:209], v[218:221], v[116:119]
	v_mfma_f32_16x16x32_bf16 v[104:107], v[198:201], v[222:225], v[104:107]
	v_mfma_f32_16x16x32_bf16 v[100:103], v[206:209], v[222:225], v[100:103]
	v_mfma_f32_16x16x32_bf16 v[88:91], v[198:201], v[234:237], v[88:91]
	v_mfma_f32_16x16x32_bf16 v[84:87], v[206:209], v[234:237], v[84:87]
	v_mfma_f32_16x16x32_bf16 v[72:75], v[198:201], v[238:241], v[72:75]
	v_mfma_f32_16x16x32_bf16 v[68:71], v[206:209], v[238:241], v[68:71]
	s_barrier
	v_lshl_add_u64 v[140:141], s[84:85], 0, v[158:159]
	s_add_i32 s84, s67, s3
	s_mov_b32 m0, s84
	global_load_lds_dwordx4 v[140:141], off
	v_lshl_add_u64 v[242:243], v[140:141], 0, s[0:1]
	s_add_i32 m0, s84, 0x2000
	s_add_i32 s84, s72, s3
	global_load_lds_dwordx4 v[242:243], off
	v_lshl_add_u64 v[242:243], v[140:141], 0, s[12:13]
	s_mov_b32 m0, s84
	s_nop 0
	global_load_lds_dwordx4 v[242:243], off
	v_lshl_add_u64 v[242:243], v[140:141], 0, s[14:15]
	s_add_i32 m0, s84, 0x2000
	s_nop 0
	global_load_lds_dwordx4 v[242:243], off
	ds_read_b128 v[210:213], v153 offset:16384
	ds_read_b128 v[214:217], v153 offset:18432
	ds_read_b128 v[218:221], v154 offset:16384
	ds_read_b128 v[222:225], v154 offset:18432
	ds_read_b128 v[226:229], v153 offset:20480
	ds_read_b128 v[230:233], v153 offset:22528
	ds_read_b128 v[234:237], v154 offset:20480
	ds_read_b128 v[238:241], v154 offset:22528
	s_waitcnt vmcnt(4)
	s_waitcnt lgkmcnt(0)
	s_barrier
	v_mfma_f32_16x16x32_bf16 v[64:67], v[168:171], v[210:213], v[64:67]
	v_mfma_f32_16x16x32_bf16 v[60:63], v[178:181], v[210:213], v[60:63]
	v_mfma_f32_16x16x32_bf16 v[48:51], v[168:171], v[214:217], v[48:51]
	v_mfma_f32_16x16x32_bf16 v[44:47], v[178:181], v[214:217], v[44:47]
	v_mfma_f32_16x16x32_bf16 v[32:35], v[168:171], v[226:229], v[32:35]
	v_mfma_f32_16x16x32_bf16 v[28:31], v[178:181], v[226:229], v[28:31]
	v_mfma_f32_16x16x32_bf16 v[16:19], v[168:171], v[230:233], v[16:19]
	v_mfma_f32_16x16x32_bf16 v[12:15], v[178:181], v[230:233], v[12:15]
	v_mfma_f32_16x16x32_bf16 v[64:67], v[174:177], v[218:221], v[64:67]
	v_mfma_f32_16x16x32_bf16 v[60:63], v[182:185], v[218:221], v[60:63]
	v_mfma_f32_16x16x32_bf16 v[48:51], v[174:177], v[222:225], v[48:51]
	v_mfma_f32_16x16x32_bf16 v[44:47], v[182:185], v[222:225], v[44:47]
	v_mfma_f32_16x16x32_bf16 v[32:35], v[174:177], v[234:237], v[32:35]
	v_mfma_f32_16x16x32_bf16 v[28:31], v[182:185], v[234:237], v[28:31]
	v_mfma_f32_16x16x32_bf16 v[16:19], v[174:177], v[238:241], v[16:19]
	v_mfma_f32_16x16x32_bf16 v[12:15], v[182:185], v[238:241], v[12:15]
	v_mfma_f32_16x16x32_bf16 v[56:59], v[194:197], v[210:213], v[56:59]
	v_mfma_f32_16x16x32_bf16 v[52:55], v[202:205], v[210:213], v[52:55]
	v_mfma_f32_16x16x32_bf16 v[40:43], v[194:197], v[214:217], v[40:43]
	v_mfma_f32_16x16x32_bf16 v[36:39], v[202:205], v[214:217], v[36:39]
	v_mfma_f32_16x16x32_bf16 v[24:27], v[194:197], v[226:229], v[24:27]
	v_mfma_f32_16x16x32_bf16 v[20:23], v[202:205], v[226:229], v[20:23]
	v_mfma_f32_16x16x32_bf16 v[8:11], v[194:197], v[230:233], v[8:11]
	v_mfma_f32_16x16x32_bf16 v[4:7], v[202:205], v[230:233], v[4:7]
	v_mfma_f32_16x16x32_bf16 v[56:59], v[198:201], v[218:221], v[56:59]
	v_mfma_f32_16x16x32_bf16 v[52:55], v[206:209], v[218:221], v[52:55]
	v_mfma_f32_16x16x32_bf16 v[40:43], v[198:201], v[222:225], v[40:43]
	v_mfma_f32_16x16x32_bf16 v[36:39], v[206:209], v[222:225], v[36:39]
	v_mfma_f32_16x16x32_bf16 v[24:27], v[198:201], v[234:237], v[24:27]
	v_mfma_f32_16x16x32_bf16 v[20:23], v[206:209], v[234:237], v[20:23]
	v_mfma_f32_16x16x32_bf16 v[8:11], v[198:201], v[238:241], v[8:11]
	v_mfma_f32_16x16x32_bf16 v[4:7], v[206:209], v[238:241], v[4:7]
	s_barrier
	s_mov_b32 m0, s34
	v_lshl_add_u64 v[242:243], s[70:71], 0, v[0:1]
	global_load_lds_dwordx4 v[242:243], off
	v_lshl_add_u64 v[244:245], v[242:243], 0, s[16:17]
	s_mov_b32 m0, s35
	s_nop 0
	global_load_lds_dwordx4 v[244:245], off
	v_lshl_add_u64 v[244:245], v[242:243], 0, s[0:1]
	s_mov_b32 m0, s38
	v_lshl_add_u64 v[242:243], v[242:243], 0, s[18:19]
	global_load_lds_dwordx4 v[244:245], off
	s_mov_b32 m0, s39
	s_nop 0
	global_load_lds_dwordx4 v[242:243], off
	ds_read_b128 v[168:171], v163
	ds_read_b128 v[174:177], v164
	ds_read_b128 v[178:181], v155
	ds_read_b128 v[182:185], v160
	ds_read_b128 v[194:197], v165
	ds_read_b128 v[198:201], v166
	ds_read_b128 v[202:205], v161
	ds_read_b128 v[206:209], v162
	ds_read_b128 v[210:213], v153 offset:32768
	ds_read_b128 v[214:217], v153 offset:34816
	ds_read_b128 v[218:221], v154 offset:32768
	ds_read_b128 v[222:225], v154 offset:34816
	ds_read_b128 v[226:229], v153 offset:36864
	ds_read_b128 v[230:233], v153 offset:38912
	ds_read_b128 v[234:237], v154 offset:36864
	ds_read_b128 v[238:241], v154 offset:38912
	s_waitcnt vmcnt(8)
	s_waitcnt lgkmcnt(0)
	s_barrier
	v_mfma_f32_16x16x32_bf16 v[128:131], v[168:171], v[210:213], v[128:131]
	v_mfma_f32_16x16x32_bf16 v[124:127], v[178:181], v[210:213], v[124:127]
	v_mfma_f32_16x16x32_bf16 v[112:115], v[168:171], v[214:217], v[112:115]
	v_mfma_f32_16x16x32_bf16 v[108:111], v[178:181], v[214:217], v[108:111]
	v_mfma_f32_16x16x32_bf16 v[96:99], v[168:171], v[226:229], v[96:99]
	v_mfma_f32_16x16x32_bf16 v[92:95], v[178:181], v[226:229], v[92:95]
	v_mfma_f32_16x16x32_bf16 v[80:83], v[168:171], v[230:233], v[80:83]
	v_mfma_f32_16x16x32_bf16 v[76:79], v[178:181], v[230:233], v[76:79]
	v_mfma_f32_16x16x32_bf16 v[128:131], v[174:177], v[218:221], v[128:131]
	v_mfma_f32_16x16x32_bf16 v[124:127], v[182:185], v[218:221], v[124:127]
	v_mfma_f32_16x16x32_bf16 v[112:115], v[174:177], v[222:225], v[112:115]
	v_mfma_f32_16x16x32_bf16 v[108:111], v[182:185], v[222:225], v[108:111]
	v_mfma_f32_16x16x32_bf16 v[96:99], v[174:177], v[234:237], v[96:99]
	v_mfma_f32_16x16x32_bf16 v[92:95], v[182:185], v[234:237], v[92:95]
	v_mfma_f32_16x16x32_bf16 v[80:83], v[174:177], v[238:241], v[80:83]
	v_mfma_f32_16x16x32_bf16 v[76:79], v[182:185], v[238:241], v[76:79]
	v_mfma_f32_16x16x32_bf16 v[120:123], v[194:197], v[210:213], v[120:123]
	v_mfma_f32_16x16x32_bf16 v[116:119], v[202:205], v[210:213], v[116:119]
	v_mfma_f32_16x16x32_bf16 v[104:107], v[194:197], v[214:217], v[104:107]
	v_mfma_f32_16x16x32_bf16 v[100:103], v[202:205], v[214:217], v[100:103]
	v_mfma_f32_16x16x32_bf16 v[88:91], v[194:197], v[226:229], v[88:91]
	v_mfma_f32_16x16x32_bf16 v[84:87], v[202:205], v[226:229], v[84:87]
	v_mfma_f32_16x16x32_bf16 v[72:75], v[194:197], v[230:233], v[72:75]
	v_mfma_f32_16x16x32_bf16 v[68:71], v[202:205], v[230:233], v[68:71]
	v_mfma_f32_16x16x32_bf16 v[120:123], v[198:201], v[218:221], v[120:123]
	v_mfma_f32_16x16x32_bf16 v[116:119], v[206:209], v[218:221], v[116:119]
	v_mfma_f32_16x16x32_bf16 v[104:107], v[198:201], v[222:225], v[104:107]
	v_mfma_f32_16x16x32_bf16 v[100:103], v[206:209], v[222:225], v[100:103]
	v_mfma_f32_16x16x32_bf16 v[88:91], v[198:201], v[234:237], v[88:91]
	v_mfma_f32_16x16x32_bf16 v[84:87], v[206:209], v[234:237], v[84:87]
	v_mfma_f32_16x16x32_bf16 v[72:75], v[198:201], v[238:241], v[72:75]
	v_mfma_f32_16x16x32_bf16 v[68:71], v[206:209], v[238:241], v[68:71]
	s_barrier
	s_add_i32 s70, s73, s3
	v_lshl_add_u64 v[242:243], v[140:141], 0, s[22:23]
	s_mov_b32 m0, s70
	global_load_lds_dwordx4 v[242:243], off
	v_lshl_add_u64 v[242:243], v[140:141], 0, s[24:25]
	s_add_i32 m0, s70, 0x2000
	s_add_i32 s70, s77, s3
	global_load_lds_dwordx4 v[242:243], off
	v_lshl_add_u64 v[242:243], v[140:141], 0, s[28:29]
	s_mov_b32 m0, s70
	v_lshl_add_u64 v[140:141], v[140:141], 0, s[36:37]
	global_load_lds_dwordx4 v[242:243], off
	s_add_i32 m0, s70, 0x2000
	s_nop 0
	global_load_lds_dwordx4 v[140:141], off
	ds_read_b128 v[210:213], v153 offset:49152
	ds_read_b128 v[214:217], v153 offset:51200
	ds_read_b128 v[218:221], v154 offset:49152
	ds_read_b128 v[222:225], v154 offset:51200
	ds_read_b128 v[226:229], v153 offset:53248
	ds_read_b128 v[230:233], v153 offset:55296
	ds_read_b128 v[234:237], v154 offset:53248
	ds_read_b128 v[238:241], v154 offset:55296
	s_waitcnt vmcnt(4)
	s_waitcnt lgkmcnt(0)
	s_barrier
	v_mfma_f32_16x16x32_bf16 v[64:67], v[168:171], v[210:213], v[64:67]
	v_mfma_f32_16x16x32_bf16 v[60:63], v[178:181], v[210:213], v[60:63]
	v_mfma_f32_16x16x32_bf16 v[48:51], v[168:171], v[214:217], v[48:51]
	v_mfma_f32_16x16x32_bf16 v[44:47], v[178:181], v[214:217], v[44:47]
	v_mfma_f32_16x16x32_bf16 v[32:35], v[168:171], v[226:229], v[32:35]
	v_mfma_f32_16x16x32_bf16 v[28:31], v[178:181], v[226:229], v[28:31]
	v_mfma_f32_16x16x32_bf16 v[16:19], v[168:171], v[230:233], v[16:19]
	v_mfma_f32_16x16x32_bf16 v[12:15], v[178:181], v[230:233], v[12:15]
	v_mfma_f32_16x16x32_bf16 v[64:67], v[174:177], v[218:221], v[64:67]
	v_mfma_f32_16x16x32_bf16 v[60:63], v[182:185], v[218:221], v[60:63]
	v_mfma_f32_16x16x32_bf16 v[48:51], v[174:177], v[222:225], v[48:51]
	v_mfma_f32_16x16x32_bf16 v[44:47], v[182:185], v[222:225], v[44:47]
	v_mfma_f32_16x16x32_bf16 v[32:35], v[174:177], v[234:237], v[32:35]
	v_mfma_f32_16x16x32_bf16 v[28:31], v[182:185], v[234:237], v[28:31]
	v_mfma_f32_16x16x32_bf16 v[16:19], v[174:177], v[238:241], v[16:19]
	v_mfma_f32_16x16x32_bf16 v[12:15], v[182:185], v[238:241], v[12:15]
	v_mfma_f32_16x16x32_bf16 v[56:59], v[194:197], v[210:213], v[56:59]
	v_mfma_f32_16x16x32_bf16 v[52:55], v[202:205], v[210:213], v[52:55]
	v_mfma_f32_16x16x32_bf16 v[40:43], v[194:197], v[214:217], v[40:43]
	v_mfma_f32_16x16x32_bf16 v[36:39], v[202:205], v[214:217], v[36:39]
	v_mfma_f32_16x16x32_bf16 v[24:27], v[194:197], v[226:229], v[24:27]
	v_mfma_f32_16x16x32_bf16 v[20:23], v[202:205], v[226:229], v[20:23]
	v_mfma_f32_16x16x32_bf16 v[8:11], v[194:197], v[230:233], v[8:11]
	v_mfma_f32_16x16x32_bf16 v[4:7], v[202:205], v[230:233], v[4:7]
	v_mfma_f32_16x16x32_bf16 v[56:59], v[198:201], v[218:221], v[56:59]
	v_mfma_f32_16x16x32_bf16 v[52:55], v[206:209], v[218:221], v[52:55]
	v_mfma_f32_16x16x32_bf16 v[40:43], v[198:201], v[222:225], v[40:43]
	v_mfma_f32_16x16x32_bf16 v[36:39], v[206:209], v[222:225], v[36:39]
	v_mfma_f32_16x16x32_bf16 v[24:27], v[198:201], v[234:237], v[24:27]
	v_mfma_f32_16x16x32_bf16 v[20:23], v[206:209], v[234:237], v[20:23]
	v_mfma_f32_16x16x32_bf16 v[8:11], v[198:201], v[238:241], v[8:11]
	v_mfma_f32_16x16x32_bf16 v[4:7], v[206:209], v[238:241], v[4:7]
	s_barrier
	s_add_i32 s83, s83, 2
	s_add_u32 s68, s68, 0x100
	s_addc_u32 s69, s69, 0
	s_cmp_gt_u32 s83, 13
	s_cbranch_scc0 .LBB0_1135
	s_and_b64 vcc, exec, s[40:41]
	s_cbranch_vccz .LBB0_1138
	s_barrier
